# P6 K-loop: closing barrier of each MFMA block signalled 4 MFMAs early (barrier round trip overlaps matrix work); on top of v9
# baseline (speedup 1.0000x reference)
.LBB0_731:
	ds_read_b128 v[148:151], v156
	ds_read_b128 v[160:163], v156 offset:1024
	ds_read_b128 v[164:167], v156 offset:2048
	ds_read_b128 v[168:171], v156 offset:3072
	ds_read_b128 v[176:179], v157
	ds_read_b128 v[180:183], v157 offset:1024
	ds_read_b128 v[184:187], v157 offset:2048
	ds_read_b128 v[188:191], v157 offset:3072
	s_add_u32 s22, s0, 0xfff00080
	s_addc_u32 s23, s1, -1
	s_cmp_eq_u32 s61, 60
	s_cselect_b32 s25, s5, s23
	s_cselect_b32 s24, s57, s22
	s_cselect_b32 s23, s21, s60
	s_cselect_b32 s22, s58, s59
	v_lshl_add_u64 v[152:153], s[0:1], 0, v[140:141]
	s_add_i32 m0, s34, 0xc000
	ds_read_b128 v[192:195], v158
	ds_read_b128 v[196:199], v158 offset:1024
	ds_read_b128 v[200:203], v158 offset:2048
	ds_read_b128 v[204:207], v158 offset:3072
	ds_read_b128 v[208:211], v158 offset:4096
	ds_read_b128 v[212:215], v158 offset:5120
	ds_read_b128 v[216:219], v158 offset:6144
	ds_read_b128 v[220:223], v158 offset:7168
	global_load_lds_dwordx4 v[152:153], off
	v_lshl_add_u64 v[152:153], s[0:1], 0, v[142:143]
	s_add_i32 m0, s34, 0xe000
	s_nop 0
	global_load_lds_dwordx4 v[152:153], off
	s_waitcnt vmcnt(8)
	s_waitcnt lgkmcnt(0)
	s_barrier
	s_setprio 1
	s_waitcnt lgkmcnt(0)
	v_mfma_f32_16x16x32_bf16 v[126:129], v[148:151], v[192:195], v[126:129]
	v_mfma_f32_16x16x32_bf16 v[122:125], v[164:167], v[192:195], v[122:125]
	v_mfma_f32_16x16x32_bf16 v[110:113], v[148:151], v[200:203], v[110:113]
	v_mfma_f32_16x16x32_bf16 v[106:109], v[164:167], v[200:203], v[106:109]
	v_mfma_f32_16x16x32_bf16 v[94:97], v[148:151], v[208:211], v[94:97]
	v_mfma_f32_16x16x32_bf16 v[90:93], v[164:167], v[208:211], v[90:93]
	v_mfma_f32_16x16x32_bf16 v[78:81], v[148:151], v[216:219], v[78:81]
	v_mfma_f32_16x16x32_bf16 v[74:77], v[164:167], v[216:219], v[74:77]
	v_mfma_f32_16x16x32_bf16 v[126:129], v[160:163], v[196:199], v[126:129]
	v_mfma_f32_16x16x32_bf16 v[122:125], v[168:171], v[196:199], v[122:125]
	v_mfma_f32_16x16x32_bf16 v[110:113], v[160:163], v[204:207], v[110:113]
	v_mfma_f32_16x16x32_bf16 v[106:109], v[168:171], v[204:207], v[106:109]
	v_mfma_f32_16x16x32_bf16 v[94:97], v[160:163], v[212:215], v[94:97]
	v_mfma_f32_16x16x32_bf16 v[90:93], v[168:171], v[212:215], v[90:93]
	v_mfma_f32_16x16x32_bf16 v[78:81], v[160:163], v[220:223], v[78:81]
	v_mfma_f32_16x16x32_bf16 v[74:77], v[168:171], v[220:223], v[74:77]
	s_setprio 0
	s_setprio 1
	v_mfma_f32_16x16x32_bf16 v[118:121], v[176:179], v[192:195], v[118:121]
	v_mfma_f32_16x16x32_bf16 v[114:117], v[184:187], v[192:195], v[114:117]
	v_mfma_f32_16x16x32_bf16 v[102:105], v[176:179], v[200:203], v[102:105]
	v_mfma_f32_16x16x32_bf16 v[98:101], v[184:187], v[200:203], v[98:101]
	v_mfma_f32_16x16x32_bf16 v[86:89], v[176:179], v[208:211], v[86:89]
	v_mfma_f32_16x16x32_bf16 v[82:85], v[184:187], v[208:211], v[82:85]
	v_mfma_f32_16x16x32_bf16 v[70:73], v[176:179], v[216:219], v[70:73]
	v_mfma_f32_16x16x32_bf16 v[66:69], v[184:187], v[216:219], v[66:69]
	v_mfma_f32_16x16x32_bf16 v[118:121], v[180:183], v[196:199], v[118:121]
	v_mfma_f32_16x16x32_bf16 v[114:117], v[188:191], v[196:199], v[114:117]
	v_mfma_f32_16x16x32_bf16 v[102:105], v[180:183], v[204:207], v[102:105]
	v_mfma_f32_16x16x32_bf16 v[98:101], v[188:191], v[204:207], v[98:101]
	s_setprio 0
	s_barrier
	v_mfma_f32_16x16x32_bf16 v[86:89], v[180:183], v[212:215], v[86:89]
	v_mfma_f32_16x16x32_bf16 v[82:85], v[188:191], v[212:215], v[82:85]
	v_mfma_f32_16x16x32_bf16 v[70:73], v[180:183], v[220:223], v[70:73]
	v_mfma_f32_16x16x32_bf16 v[66:69], v[188:191], v[220:223], v[66:69]
	s_add_i32 s62, s44, s31
	v_lshl_add_u64 v[152:153], s[22:23], 0, v[136:137]
	s_mov_b32 m0, s62
	ds_read_b128 v[192:195], v158 offset:16384
	ds_read_b128 v[196:199], v158 offset:17408
	ds_read_b128 v[200:203], v158 offset:18432
	ds_read_b128 v[204:207], v158 offset:19456
	ds_read_b128 v[208:211], v158 offset:20480
	ds_read_b128 v[212:215], v158 offset:21504
	ds_read_b128 v[216:219], v158 offset:22528
	ds_read_b128 v[220:223], v158 offset:23552
	global_load_lds_dwordx4 v[152:153], off
	s_add_i32 m0, s62, 0x2000
	s_add_u32 s62, s22, 0x100000
	v_lshl_add_u64 v[172:173], s[22:23], 0, v[130:131]
	s_addc_u32 s63, s23, 0
	s_add_i32 s64, s45, s31
	global_load_lds_dwordx4 v[172:173], off
	v_lshl_add_u64 v[224:225], s[62:63], 0, v[136:137]
	s_mov_b32 m0, s64
	v_lshl_add_u64 v[226:227], s[24:25], 0, v[132:133]
	global_load_lds_dwordx4 v[224:225], off
	v_lshl_add_u64 v[224:225], s[62:63], 0, v[130:131]
	s_add_i32 m0, s64, 0x2000
	s_nop 0
	global_load_lds_dwordx4 v[224:225], off
	v_lshl_add_u64 v[224:225], s[24:25], 0, v[138:139]
	s_mov_b32 m0, s34
	s_nop 0
	global_load_lds_dwordx4 v[224:225], off
	s_mov_b32 m0, s35
	s_nop 0
	global_load_lds_dwordx4 v[226:227], off
	s_waitcnt vmcnt(8)
	s_waitcnt lgkmcnt(0)
	s_barrier
	s_setprio 1
	s_waitcnt lgkmcnt(0)
	v_mfma_f32_16x16x32_bf16 v[62:65], v[148:151], v[192:195], v[62:65]
	v_mfma_f32_16x16x32_bf16 v[58:61], v[164:167], v[192:195], v[58:61]
	v_mfma_f32_16x16x32_bf16 v[46:49], v[148:151], v[200:203], v[46:49]
	v_mfma_f32_16x16x32_bf16 v[42:45], v[164:167], v[200:203], v[42:45]
	v_mfma_f32_16x16x32_bf16 v[30:33], v[148:151], v[208:211], v[30:33]
	v_mfma_f32_16x16x32_bf16 v[26:29], v[164:167], v[208:211], v[26:29]
	v_mfma_f32_16x16x32_bf16 v[14:17], v[148:151], v[216:219], v[14:17]
	v_mfma_f32_16x16x32_bf16 v[10:13], v[164:167], v[216:219], v[10:13]
	v_mfma_f32_16x16x32_bf16 v[62:65], v[160:163], v[196:199], v[62:65]
	v_mfma_f32_16x16x32_bf16 v[58:61], v[168:171], v[196:199], v[58:61]
	v_mfma_f32_16x16x32_bf16 v[46:49], v[160:163], v[204:207], v[46:49]
	v_mfma_f32_16x16x32_bf16 v[42:45], v[168:171], v[204:207], v[42:45]
	v_mfma_f32_16x16x32_bf16 v[30:33], v[160:163], v[212:215], v[30:33]
	v_mfma_f32_16x16x32_bf16 v[26:29], v[168:171], v[212:215], v[26:29]
	v_mfma_f32_16x16x32_bf16 v[14:17], v[160:163], v[220:223], v[14:17]
	v_mfma_f32_16x16x32_bf16 v[10:13], v[168:171], v[220:223], v[10:13]
	s_setprio 0
	s_setprio 1
	v_mfma_f32_16x16x32_bf16 v[54:57], v[176:179], v[192:195], v[54:57]
	v_mfma_f32_16x16x32_bf16 v[50:53], v[184:187], v[192:195], v[50:53]
	v_mfma_f32_16x16x32_bf16 v[38:41], v[176:179], v[200:203], v[38:41]
	v_mfma_f32_16x16x32_bf16 v[34:37], v[184:187], v[200:203], v[34:37]
	v_mfma_f32_16x16x32_bf16 v[22:25], v[176:179], v[208:211], v[22:25]
	v_mfma_f32_16x16x32_bf16 v[18:21], v[184:187], v[208:211], v[18:21]
	v_mfma_f32_16x16x32_bf16 v[6:9], v[176:179], v[216:219], v[6:9]
	v_mfma_f32_16x16x32_bf16 v[2:5], v[184:187], v[216:219], v[2:5]
	v_mfma_f32_16x16x32_bf16 v[54:57], v[180:183], v[196:199], v[54:57]
	v_mfma_f32_16x16x32_bf16 v[50:53], v[188:191], v[196:199], v[50:53]
	v_mfma_f32_16x16x32_bf16 v[38:41], v[180:183], v[204:207], v[38:41]
	v_mfma_f32_16x16x32_bf16 v[34:37], v[188:191], v[204:207], v[34:37]
	s_setprio 0
	s_barrier
	v_mfma_f32_16x16x32_bf16 v[22:25], v[180:183], v[212:215], v[22:25]
	v_mfma_f32_16x16x32_bf16 v[18:21], v[188:191], v[212:215], v[18:21]
	v_mfma_f32_16x16x32_bf16 v[6:9], v[180:183], v[220:223], v[6:9]
	v_mfma_f32_16x16x32_bf16 v[2:5], v[188:191], v[220:223], v[2:5]
	s_add_i32 s62, 0, 0x18000
	v_add_u32_e32 v159, s62, v135
	s_add_i32 s63, 0, 0x1c000
	ds_read_b128 v[148:151], v159
	ds_read_b128 v[160:163], v159 offset:1024
	ds_read_b128 v[164:167], v159 offset:2048
	ds_read_b128 v[168:171], v159 offset:3072
	v_add_u32_e32 v159, s63, v135
	ds_read_b128 v[176:179], v159
	ds_read_b128 v[180:183], v159 offset:1024
	ds_read_b128 v[184:187], v159 offset:2048
	ds_read_b128 v[188:191], v159 offset:3072
	s_add_u32 s24, s24, 0x100000
	s_addc_u32 s25, s25, 0
	s_mov_b32 m0, s36
	v_lshl_add_u64 v[228:229], s[24:25], 0, v[138:139]
	ds_read_b128 v[192:195], v158 offset:32768
	ds_read_b128 v[196:199], v158 offset:33792
	ds_read_b128 v[200:203], v158 offset:34816
	ds_read_b128 v[204:207], v158 offset:35840
	ds_read_b128 v[208:211], v158 offset:36864
	ds_read_b128 v[212:215], v158 offset:37888
	ds_read_b128 v[216:219], v158 offset:38912
	ds_read_b128 v[220:223], v158 offset:39936
	global_load_lds_dwordx4 v[228:229], off
	v_lshl_add_u64 v[228:229], s[24:25], 0, v[132:133]
	s_mov_b32 m0, s37
	s_nop 0
	global_load_lds_dwordx4 v[228:229], off
	s_waitcnt vmcnt(8)
	s_waitcnt lgkmcnt(0)
	s_barrier
	s_setprio 1
	s_waitcnt lgkmcnt(0)
	v_mfma_f32_16x16x32_bf16 v[126:129], v[148:151], v[192:195], v[126:129]
	v_mfma_f32_16x16x32_bf16 v[122:125], v[164:167], v[192:195], v[122:125]
	v_mfma_f32_16x16x32_bf16 v[110:113], v[148:151], v[200:203], v[110:113]
	v_mfma_f32_16x16x32_bf16 v[106:109], v[164:167], v[200:203], v[106:109]
	v_mfma_f32_16x16x32_bf16 v[94:97], v[148:151], v[208:211], v[94:97]
	v_mfma_f32_16x16x32_bf16 v[90:93], v[164:167], v[208:211], v[90:93]
	v_mfma_f32_16x16x32_bf16 v[78:81], v[148:151], v[216:219], v[78:81]
	v_mfma_f32_16x16x32_bf16 v[74:77], v[164:167], v[216:219], v[74:77]
	v_mfma_f32_16x16x32_bf16 v[126:129], v[160:163], v[196:199], v[126:129]
	v_mfma_f32_16x16x32_bf16 v[122:125], v[168:171], v[196:199], v[122:125]
	v_mfma_f32_16x16x32_bf16 v[110:113], v[160:163], v[204:207], v[110:113]
	v_mfma_f32_16x16x32_bf16 v[106:109], v[168:171], v[204:207], v[106:109]
	v_mfma_f32_16x16x32_bf16 v[94:97], v[160:163], v[212:215], v[94:97]
	v_mfma_f32_16x16x32_bf16 v[90:93], v[168:171], v[212:215], v[90:93]
	v_mfma_f32_16x16x32_bf16 v[78:81], v[160:163], v[220:223], v[78:81]
	v_mfma_f32_16x16x32_bf16 v[74:77], v[168:171], v[220:223], v[74:77]
	s_setprio 0
	s_setprio 1
	v_mfma_f32_16x16x32_bf16 v[118:121], v[176:179], v[192:195], v[118:121]
	v_mfma_f32_16x16x32_bf16 v[114:117], v[184:187], v[192:195], v[114:117]
	v_mfma_f32_16x16x32_bf16 v[102:105], v[176:179], v[200:203], v[102:105]
	v_mfma_f32_16x16x32_bf16 v[98:101], v[184:187], v[200:203], v[98:101]
	v_mfma_f32_16x16x32_bf16 v[86:89], v[176:179], v[208:211], v[86:89]
	v_mfma_f32_16x16x32_bf16 v[82:85], v[184:187], v[208:211], v[82:85]
	v_mfma_f32_16x16x32_bf16 v[70:73], v[176:179], v[216:219], v[70:73]
	v_mfma_f32_16x16x32_bf16 v[66:69], v[184:187], v[216:219], v[66:69]
	v_mfma_f32_16x16x32_bf16 v[118:121], v[180:183], v[196:199], v[118:121]
	v_mfma_f32_16x16x32_bf16 v[114:117], v[188:191], v[196:199], v[114:117]
	v_mfma_f32_16x16x32_bf16 v[102:105], v[180:183], v[204:207], v[102:105]
	v_mfma_f32_16x16x32_bf16 v[98:101], v[188:191], v[204:207], v[98:101]
	s_setprio 0
	s_barrier
	v_mfma_f32_16x16x32_bf16 v[86:89], v[180:183], v[212:215], v[86:89]
	v_mfma_f32_16x16x32_bf16 v[82:85], v[188:191], v[212:215], v[82:85]
	v_mfma_f32_16x16x32_bf16 v[70:73], v[180:183], v[220:223], v[70:73]
	v_mfma_f32_16x16x32_bf16 v[66:69], v[188:191], v[220:223], v[66:69]
	s_add_i32 s24, s62, s31
	v_lshl_add_u64 v[152:153], v[152:153], 0, s[16:17]
	s_mov_b32 m0, s24
	ds_read_b128 v[192:195], v158 offset:49152
	ds_read_b128 v[196:199], v158 offset:50176
	ds_read_b128 v[200:203], v158 offset:51200
	ds_read_b128 v[204:207], v158 offset:52224
	ds_read_b128 v[208:211], v158 offset:53248
	ds_read_b128 v[212:215], v158 offset:54272
	ds_read_b128 v[216:219], v158 offset:55296
	ds_read_b128 v[220:223], v158 offset:56320
	global_load_lds_dwordx4 v[152:153], off
	s_add_i32 m0, s24, 0x2000
	s_add_u32 s22, s22, 0x100080
	v_lshl_add_u64 v[152:153], v[172:173], 0, s[16:17]
	s_addc_u32 s23, s23, 0
	s_add_i32 s24, s63, s31
	global_load_lds_dwordx4 v[152:153], off
	v_lshl_add_u64 v[152:153], s[22:23], 0, v[136:137]
	s_mov_b32 m0, s24
	s_nop 0
	global_load_lds_dwordx4 v[152:153], off
	v_lshl_add_u64 v[152:153], s[22:23], 0, v[130:131]
	s_add_i32 m0, s24, 0x2000
	s_nop 0
	global_load_lds_dwordx4 v[152:153], off
	v_lshl_add_u64 v[152:153], v[224:225], 0, s[16:17]
	s_mov_b32 m0, s40
	s_nop 0
	global_load_lds_dwordx4 v[152:153], off
	v_lshl_add_u64 v[152:153], v[226:227], 0, s[16:17]
	s_mov_b32 m0, s41
	s_nop 0
	global_load_lds_dwordx4 v[152:153], off
	s_waitcnt vmcnt(8)
	s_waitcnt lgkmcnt(0)
	s_barrier
	s_setprio 1
	s_waitcnt lgkmcnt(0)
	v_mfma_f32_16x16x32_bf16 v[62:65], v[148:151], v[192:195], v[62:65]
	v_mfma_f32_16x16x32_bf16 v[58:61], v[164:167], v[192:195], v[58:61]
	v_mfma_f32_16x16x32_bf16 v[46:49], v[148:151], v[200:203], v[46:49]
	v_mfma_f32_16x16x32_bf16 v[42:45], v[164:167], v[200:203], v[42:45]
	v_mfma_f32_16x16x32_bf16 v[30:33], v[148:151], v[208:211], v[30:33]
	v_mfma_f32_16x16x32_bf16 v[26:29], v[164:167], v[208:211], v[26:29]
	v_mfma_f32_16x16x32_bf16 v[14:17], v[148:151], v[216:219], v[14:17]
	v_mfma_f32_16x16x32_bf16 v[10:13], v[164:167], v[216:219], v[10:13]
	v_mfma_f32_16x16x32_bf16 v[62:65], v[160:163], v[196:199], v[62:65]
	v_mfma_f32_16x16x32_bf16 v[58:61], v[168:171], v[196:199], v[58:61]
	v_mfma_f32_16x16x32_bf16 v[46:49], v[160:163], v[204:207], v[46:49]
	v_mfma_f32_16x16x32_bf16 v[42:45], v[168:171], v[204:207], v[42:45]
	v_mfma_f32_16x16x32_bf16 v[30:33], v[160:163], v[212:215], v[30:33]
	v_mfma_f32_16x16x32_bf16 v[26:29], v[168:171], v[212:215], v[26:29]
	v_mfma_f32_16x16x32_bf16 v[14:17], v[160:163], v[220:223], v[14:17]
	v_mfma_f32_16x16x32_bf16 v[10:13], v[168:171], v[220:223], v[10:13]
	s_setprio 0
	s_setprio 1
	v_mfma_f32_16x16x32_bf16 v[54:57], v[176:179], v[192:195], v[54:57]
	v_mfma_f32_16x16x32_bf16 v[50:53], v[184:187], v[192:195], v[50:53]
	v_mfma_f32_16x16x32_bf16 v[38:41], v[176:179], v[200:203], v[38:41]
	v_mfma_f32_16x16x32_bf16 v[34:37], v[184:187], v[200:203], v[34:37]
	v_mfma_f32_16x16x32_bf16 v[22:25], v[176:179], v[208:211], v[22:25]
	v_mfma_f32_16x16x32_bf16 v[18:21], v[184:187], v[208:211], v[18:21]
	v_mfma_f32_16x16x32_bf16 v[6:9], v[176:179], v[216:219], v[6:9]
	v_mfma_f32_16x16x32_bf16 v[2:5], v[184:187], v[216:219], v[2:5]
	v_mfma_f32_16x16x32_bf16 v[54:57], v[180:183], v[196:199], v[54:57]
	v_mfma_f32_16x16x32_bf16 v[50:53], v[188:191], v[196:199], v[50:53]
	v_mfma_f32_16x16x32_bf16 v[38:41], v[180:183], v[204:207], v[38:41]
	v_mfma_f32_16x16x32_bf16 v[34:37], v[188:191], v[204:207], v[34:37]
	s_setprio 0
	s_barrier
	v_mfma_f32_16x16x32_bf16 v[22:25], v[180:183], v[212:215], v[22:25]
	v_mfma_f32_16x16x32_bf16 v[18:21], v[188:191], v[212:215], v[18:21]
	v_mfma_f32_16x16x32_bf16 v[6:9], v[180:183], v[220:223], v[6:9]
	v_mfma_f32_16x16x32_bf16 v[2:5], v[188:191], v[220:223], v[2:5]
	s_add_i32 s61, s61, 2
	s_add_u32 s0, s0, 0x100
	s_addc_u32 s1, s1, 0
	s_add_u32 s59, s59, 0x100
	s_addc_u32 s60, s60, 0
	s_cmp_gt_u32 s61, 61
	s_cbranch_scc0 .LBB0_731
	v_and_b32_e32 v165, 3, v174
	v_lshrrev_b32_e32 v170, 2, v174
	v_lshlrev_b32_e32 v164, 6, v165
	v_and_or_b32 v164, v174, 60, v164
	v_and_b32_e32 v171, 15, v174
	v_sub_u32_e32 v170, v170, v171
	v_lshrrev_b32_e32 v171, 4, v174
	v_sub_u32_e32 v165, v165, v171
	v_mul_i32_i24_e32 v170, 0xac00, v170
	v_lshl_add_u32 v166, v165, 4, v170
	v_ashrrev_i32_e32 v167, 31, v166
	s_lshl_b32 s5, s56, 8
	s_add_i32 s5, s5, s39
	v_or_b32_e32 v159, s5, v1
	v_cmp_lt_i32_e64 s[0:1], s46, v159
	s_and_b64 s[22:23], s[0:1], s[18:19]
	v_mov_b64_e32 v[150:151], 0
	s_and_saveexec_b64 s[0:1], s[22:23]
	v_add_u32_e32 v148, 0xffffe000, v159
	v_lshrrev_b32_e32 v148, 2, v148
	v_and_b32_e32 v148, 0x3ffffff2, v148
	v_add_u32_e32 v150, v148, v154
	v_mov_b64_e32 v[148:149], s[10:11]
	v_mad_u64_u32 v[150:151], s[22:23], v150, s47, v[148:149]
	s_or_b64 exec, exec, s[0:1]
	v_lshl_or_b32 v148, s55, 8, v155
	v_mov_b64_e32 v[152:153], s[6:7]
	v_ashrrev_i32_e32 v149, 31, v148
	v_mad_i64_i32 v[152:153], s[0:1], v159, s48, v[152:153]
	v_lshl_add_u64 v[152:153], v[148:149], 1, v[152:153]
	v_cmp_ne_u64_e64 s[0:1], 0, v[150:151]
	v_lshl_add_u64 v[150:151], v[148:149], 2, v[150:151]
	v_cvt_pk_bf16_f32 v160, v126, v127
	v_cvt_pk_bf16_f32 v161, v128, v129
	v_cvt_pk_bf16_f32 v162, v122, v123
	v_cvt_pk_bf16_f32 v163, v124, v125
	ds_bpermute_b32 v160, v164, v160
	ds_bpermute_b32 v161, v164, v161
	ds_bpermute_b32 v162, v164, v162
	ds_bpermute_b32 v163, v164, v163
	v_lshl_add_u64 v[168:169], v[166:167], 0, v[152:153]
	s_waitcnt lgkmcnt(0)
	global_store_dwordx4 v[168:169], v[160:163], off
	s_and_saveexec_b64 s[22:23], s[0:1]
	s_cbranch_execz .LBB0_736
	global_store_dwordx4 v[150:151], v[126:129], off
	global_store_dwordx4 v[150:151], v[122:125], off offset:16
